# v25 with the second half of the exp block interleaved with the first half's bf16 packing and row-sum adds in all six attention V bodies
# speedup vs baseline: 1.0041x; 1.0038x over previous
; #define SBAR() __builtin_amdgcn_sched_barrier(0)
; #define PK4(P, BASE, OUT) do { u32x4 w = {cvtpk_a(P[BASE + 0], P[BASE + 1]), cvtpk_a(P[BASE + 2], P[BASE + 3]), cvtpk_a(P[BASE + 4], P[BASE + 5]), cvtpk_a(P[BASE + 6], P[BASE + 7])}; \
;     OUT = *reinterpret_cast<bf16x8*>(&w); } while (0)
; #define SWAIT() asm volatile("s_waitcnt vmcnt(3)" ::: "memory")
; __device__ __forceinline__ float exp_pack(f32x16& p0, f32x16& p1, bf16x8& pa0, bf16x8& pa1, bf16x8& pa2, bf16x8& pa3) {
; #pragma unroll
;     for (int r = 0; r < 16; ++r) p0[r] = __builtin_amdgcn_exp2f(p0[r]);
; #pragma unroll
;     for (int r = 0; r < 16; ++r) p1[r] = __builtin_amdgcn_exp2f(p1[r]);
;     SBAR(); asm volatile("s_nop 1" ::: "memory"); SBAR();
;     ...
;     PK4(p0, 0, pa0); PK4(p0, 8, pa1); PK4(p1, 0, pa2); PK4(p1, 8, pa3);
;     ...
;     float ps0 = p0[0], ps1 = p1[0];
; #pragma unroll
;     for (int r = 1; r < 16; ++r) { ps0 += p0[r]; ps1 += p1[r]; }
;     float ps = ps0 + ps1;
;     { auto rr = __builtin_amdgcn_permlane32_swap(__float_as_uint(ps), __float_as_uint(ps), false, false);
;       ps = __uint_as_float(rr[0]) + __uint_as_float(rr[1]); }
;     return ps;
; template <bool MLA>
; __device__ __forceinline__ void attn_core(const bf16_t* __restrict__ Qb, const bf16_t* __restrict__ Kh, const bf16_t* __restrict__ Vh, int seq, char* lds,
;                                           f32x16 (&o)[Cfg<MLA>::NCB], const int wid  , const int g  ) {
;     ...
;         SWAIT(); if (j + 2 < NT) SWRITE(((j + 2) % 3) * SHM_K, ((j + 2) & 3) * SHM_V, SE);
.LBB0_1162:
	v_exp_f32_e32 v96, v96
	v_exp_f32_e32 v97, v97
	v_exp_f32_e32 v98, v98
	v_exp_f32_e32 v99, v99
	v_exp_f32_e32 v100, v100
	v_exp_f32_e32 v101, v101
	v_exp_f32_e32 v102, v102
	v_exp_f32_e32 v103, v103
	v_exp_f32_e32 v104, v104
	v_exp_f32_e32 v105, v105
	v_exp_f32_e32 v106, v106
	v_exp_f32_e32 v107, v107
	v_exp_f32_e32 v108, v108
	v_exp_f32_e32 v109, v109
	v_exp_f32_e32 v110, v110
	v_exp_f32_e32 v111, v111
	v_exp_f32_e32 v80, v80
	v_cvt_pk_bf16_f32 v180, v96, v97
	v_cvt_pk_bf16_f32 v176, v104, v105
	v_exp_f32_e32 v81, v81
	v_add_f32_e32 v96, v96, v97
	v_exp_f32_e32 v82, v82
	v_add_f32_e32 v104, v104, v105
	v_add_f32_e32 v96, v98, v96
	v_exp_f32_e32 v83, v83
	v_add_f32_e32 v104, v106, v104
	v_exp_f32_e32 v84, v84
	v_cvt_pk_bf16_f32 v181, v98, v99
	v_add_f32_e32 v96, v99, v96
	v_exp_f32_e32 v85, v85
	v_add_f32_e32 v104, v107, v104
	v_exp_f32_e32 v86, v86
	v_cvt_pk_bf16_f32 v177, v106, v107
	v_add_f32_e32 v96, v100, v96
	v_exp_f32_e32 v87, v87
	v_add_f32_e32 v104, v108, v104
	v_exp_f32_e32 v88, v88
	v_cvt_pk_bf16_f32 v182, v100, v101
	v_add_f32_e32 v96, v101, v96
	v_exp_f32_e32 v89, v89
	v_add_f32_e32 v104, v109, v104
	v_exp_f32_e32 v90, v90
	v_cvt_pk_bf16_f32 v178, v108, v109
	v_add_f32_e32 v96, v102, v96
	v_exp_f32_e32 v91, v91
	v_add_f32_e32 v104, v110, v104
	v_exp_f32_e32 v92, v92
	v_cvt_pk_bf16_f32 v183, v102, v103
	v_add_f32_e32 v96, v103, v96
	v_exp_f32_e32 v93, v93
	v_add_f32_e32 v104, v111, v104
	v_exp_f32_e32 v94, v94
	v_cvt_pk_bf16_f32 v179, v110, v111
	v_add_f32_e32 v96, v96, v104
	v_exp_f32_e32 v95, v95
	v_cvt_pk_bf16_f32 v172, v80, v81
	v_cvt_pk_bf16_f32 v168, v88, v89
	v_add_f32_e32 v80, v80, v81
	v_add_f32_e32 v88, v88, v89
	v_add_f32_e32 v80, v82, v80
	v_add_f32_e32 v88, v90, v88
	v_cvt_pk_bf16_f32 v173, v82, v83
	v_add_f32_e32 v80, v83, v80
	v_add_f32_e32 v88, v91, v88
	v_cvt_pk_bf16_f32 v169, v90, v91
	v_add_f32_e32 v80, v84, v80
	v_add_f32_e32 v88, v92, v88
	v_cvt_pk_bf16_f32 v174, v84, v85
	v_add_f32_e32 v80, v85, v80
	v_add_f32_e32 v88, v93, v88
	v_cvt_pk_bf16_f32 v170, v92, v93
	v_add_f32_e32 v80, v86, v80
	v_add_f32_e32 v88, v94, v88
	v_cvt_pk_bf16_f32 v175, v86, v87
	v_add_f32_e32 v80, v87, v80
	v_add_f32_e32 v88, v95, v88
	v_cvt_pk_bf16_f32 v171, v94, v95
	v_add_f32_e32 v80, v80, v88
	v_add_f32_e32 v185, v80, v96
	s_waitcnt vmcnt(3)
	s_cmpk_gt_u32 s95, 0x81
	s_cbranch_scc1 .LBB0_1164
	s_add_i32 s0, s51, 0x8000
	s_and_b32 s0, s0, 0x8000
	s_add_i32 s0, s0, 0
	v_add_u32_e32 v80, s0, v210
	s_waitcnt vmcnt(5)
	ds_write_b128 v80, v[132:135]
	v_add_u32_e32 v80, s0, v211
	s_add_i32 s0, s94, 0xffff
	s_mul_i32 s1, s0, 0xab
	s_bfe_u32 s1, s1, 0x70009
	s_mul_i32 s1, s1, 3
	s_sub_i32 s0, s0, s1
	s_and_b32 s0, s0, 0xff
	s_mulk_i32 s0, 0x2400
	s_waitcnt vmcnt(4)
	ds_write_b128 v80, v[128:131]
	v_add_u32_e32 v80, s0, v212
	s_waitcnt vmcnt(3)
	ds_write_b128 v80, v[136:139]

; #define SBAR() __builtin_amdgcn_sched_barrier(0)
; #define PK4(P, BASE, OUT) do { u32x4 w = {cvtpk_a(P[BASE + 0], P[BASE + 1]), cvtpk_a(P[BASE + 2], P[BASE + 3]), cvtpk_a(P[BASE + 4], P[BASE + 5]), cvtpk_a(P[BASE + 6], P[BASE + 7])}; \
;     OUT = *reinterpret_cast<bf16x8*>(&w); } while (0)
; #define SWAIT() asm volatile("s_waitcnt vmcnt(3)" ::: "memory")
; __device__ __forceinline__ float exp_pack(f32x16& p0, f32x16& p1, bf16x8& pa0, bf16x8& pa1, bf16x8& pa2, bf16x8& pa3) {
; #pragma unroll
;     for (int r = 0; r < 16; ++r) p0[r] = __builtin_amdgcn_exp2f(p0[r]);
; #pragma unroll
;     for (int r = 0; r < 16; ++r) p1[r] = __builtin_amdgcn_exp2f(p1[r]);
;     SBAR(); asm volatile("s_nop 1" ::: "memory"); SBAR();
;     ...
;     PK4(p0, 0, pa0); PK4(p0, 8, pa1); PK4(p1, 0, pa2); PK4(p1, 8, pa3);
;     ...
;     float ps0 = p0[0], ps1 = p1[0];
; #pragma unroll
;     for (int r = 1; r < 16; ++r) { ps0 += p0[r]; ps1 += p1[r]; }
;     float ps = ps0 + ps1;
;     { auto rr = __builtin_amdgcn_permlane32_swap(__float_as_uint(ps), __float_as_uint(ps), false, false);
;       ps = __uint_as_float(rr[0]) + __uint_as_float(rr[1]); }
;     return ps;
; template <bool MLA>
; __device__ __forceinline__ void attn_core(const bf16_t* __restrict__ Qb, const bf16_t* __restrict__ Kh, const bf16_t* __restrict__ Vh, int seq, char* lds,
;                                           f32x16 (&o)[Cfg<MLA>::NCB], const int wid  , const int g  ) {
;     ...
;         SWAIT(); if (j + 3 < NT) SWRITE(((j + 3) % 3) * SHM_K, ((j + 3) & 3) * SHM_V, SO);
.LBB0_1169:
	v_exp_f32_e32 v96, v96
	v_exp_f32_e32 v97, v97
	v_exp_f32_e32 v98, v98
	v_exp_f32_e32 v99, v99
	v_exp_f32_e32 v100, v100
	v_exp_f32_e32 v101, v101
	v_exp_f32_e32 v102, v102
	v_exp_f32_e32 v103, v103
	v_exp_f32_e32 v104, v104
	v_exp_f32_e32 v105, v105
	v_exp_f32_e32 v106, v106
	v_exp_f32_e32 v107, v107
	v_exp_f32_e32 v108, v108
	v_exp_f32_e32 v109, v109
	v_exp_f32_e32 v110, v110
	v_exp_f32_e32 v111, v111
	v_exp_f32_e32 v80, v80
	v_cvt_pk_bf16_f32 v180, v96, v97
	v_cvt_pk_bf16_f32 v176, v104, v105
	v_exp_f32_e32 v81, v81
	v_add_f32_e32 v96, v96, v97
	v_exp_f32_e32 v82, v82
	v_add_f32_e32 v104, v104, v105
	v_add_f32_e32 v96, v98, v96
	v_exp_f32_e32 v83, v83
	v_add_f32_e32 v104, v106, v104
	v_exp_f32_e32 v84, v84
	v_cvt_pk_bf16_f32 v181, v98, v99
	v_add_f32_e32 v96, v99, v96
	v_exp_f32_e32 v85, v85
	v_add_f32_e32 v104, v107, v104
	v_exp_f32_e32 v86, v86
	v_cvt_pk_bf16_f32 v177, v106, v107
	v_add_f32_e32 v96, v100, v96
	v_exp_f32_e32 v87, v87
	v_add_f32_e32 v104, v108, v104
	v_exp_f32_e32 v88, v88
	v_cvt_pk_bf16_f32 v182, v100, v101
	v_add_f32_e32 v96, v101, v96
	v_exp_f32_e32 v89, v89
	v_add_f32_e32 v104, v109, v104
	v_exp_f32_e32 v90, v90
	v_cvt_pk_bf16_f32 v178, v108, v109
	v_add_f32_e32 v96, v102, v96
	v_exp_f32_e32 v91, v91
	v_add_f32_e32 v104, v110, v104
	v_exp_f32_e32 v92, v92
	v_cvt_pk_bf16_f32 v183, v102, v103
	v_add_f32_e32 v96, v103, v96
	v_exp_f32_e32 v93, v93
	v_add_f32_e32 v104, v111, v104
	v_exp_f32_e32 v94, v94
	v_cvt_pk_bf16_f32 v179, v110, v111
	v_add_f32_e32 v96, v96, v104
	v_exp_f32_e32 v95, v95
	v_cvt_pk_bf16_f32 v172, v80, v81
	v_cvt_pk_bf16_f32 v168, v88, v89
	v_add_f32_e32 v80, v80, v81
	v_add_f32_e32 v88, v88, v89
	v_add_f32_e32 v80, v82, v80
	v_add_f32_e32 v88, v90, v88
	v_cvt_pk_bf16_f32 v173, v82, v83
	v_add_f32_e32 v80, v83, v80
	v_add_f32_e32 v88, v91, v88
	v_cvt_pk_bf16_f32 v169, v90, v91
	v_add_f32_e32 v80, v84, v80
	v_add_f32_e32 v88, v92, v88
	v_cvt_pk_bf16_f32 v174, v84, v85
	v_add_f32_e32 v80, v85, v80
	v_add_f32_e32 v88, v93, v88
	v_cvt_pk_bf16_f32 v170, v92, v93
	v_add_f32_e32 v80, v86, v80
	v_add_f32_e32 v88, v94, v88
	v_cvt_pk_bf16_f32 v175, v86, v87
	v_add_f32_e32 v80, v87, v80
	v_add_f32_e32 v88, v95, v88
	v_cvt_pk_bf16_f32 v171, v94, v95
	v_add_f32_e32 v80, v80, v88
	v_add_f32_e32 v80, v80, v96
	s_waitcnt vmcnt(3)
	s_cmpk_gt_u32 s95, 0x80
	s_cbranch_scc1 .LBB0_1149
	s_add_i32 s0, s96, 0
	v_add_u32_e32 v82, s0, v210
	s_waitcnt vmcnt(5)
	ds_write_b128 v82, v[140:143]
	v_add_u32_e32 v82, s0, v211
	s_mul_i32 s0, s94, 0xab
	s_bfe_u32 s0, s0, 0x70009
	s_mul_i32 s0, s0, 3
	s_sub_i32 s0, s94, s0
	s_and_b32 s0, s0, 0xff
	s_mulk_i32 s0, 0x2400
	s_waitcnt vmcnt(4)
	ds_write_b128 v82, v[144:147]
	v_add_u32_e32 v82, s0, v212
	s_waitcnt vmcnt(3)
	ds_write_b128 v82, v[148:151]
	s_branch .LBB0_1149

; #define SBAR() __builtin_amdgcn_sched_barrier(0)
; #define PK4(P, BASE, OUT) do { u32x4 w = {cvtpk_a(P[BASE + 0], P[BASE + 1]), cvtpk_a(P[BASE + 2], P[BASE + 3]), cvtpk_a(P[BASE + 4], P[BASE + 5]), cvtpk_a(P[BASE + 6], P[BASE + 7])}; \
;     OUT = *reinterpret_cast<bf16x8*>(&w); } while (0)
; #define SWAIT() asm volatile("s_waitcnt vmcnt(3)" ::: "memory")
; __device__ __forceinline__ float exp_pack(f32x16& p0, f32x16& p1, bf16x8& pa0, bf16x8& pa1, bf16x8& pa2, bf16x8& pa3) {
; #pragma unroll
;     for (int r = 0; r < 16; ++r) p0[r] = __builtin_amdgcn_exp2f(p0[r]);
; #pragma unroll
;     for (int r = 0; r < 16; ++r) p1[r] = __builtin_amdgcn_exp2f(p1[r]);
;     SBAR(); asm volatile("s_nop 1" ::: "memory"); SBAR();
;     ...
;     PK4(p0, 0, pa0); PK4(p0, 8, pa1); PK4(p1, 0, pa2); PK4(p1, 8, pa3);
;     ...
;     float ps0 = p0[0], ps1 = p1[0];
; #pragma unroll
;     for (int r = 1; r < 16; ++r) { ps0 += p0[r]; ps1 += p1[r]; }
;     float ps = ps0 + ps1;
;     { auto rr = __builtin_amdgcn_permlane32_swap(__float_as_uint(ps), __float_as_uint(ps), false, false);
;       ps = __uint_as_float(rr[0]) + __uint_as_float(rr[1]); }
;     return ps;
; template <bool MLA>
; __device__ __forceinline__ void attn_core(const bf16_t* __restrict__ Qb, const bf16_t* __restrict__ Kh, const bf16_t* __restrict__ Vh, int seq, char* lds,
;                                           f32x16 (&o)[Cfg<MLA>::NCB], const int wid  , const int g  ) {
;     ...
;         SWAIT(); if (j + 2 < NT) SWRITE(((j + 2) % 3) * SHM_K, ((j + 2) & 3) * SHM_V, SE);
.LBB0_1193:
	v_exp_f32_e32 v96, v96
	v_exp_f32_e32 v97, v97
	v_exp_f32_e32 v98, v98
	v_exp_f32_e32 v99, v99
	v_exp_f32_e32 v100, v100
	v_exp_f32_e32 v101, v101
	v_exp_f32_e32 v102, v102
	v_exp_f32_e32 v103, v103
	v_exp_f32_e32 v104, v104
	v_exp_f32_e32 v105, v105
	v_exp_f32_e32 v106, v106
	v_exp_f32_e32 v107, v107
	v_exp_f32_e32 v108, v108
	v_exp_f32_e32 v109, v109
	v_exp_f32_e32 v110, v110
	v_exp_f32_e32 v111, v111
	v_exp_f32_e32 v80, v80
	v_cvt_pk_bf16_f32 v180, v96, v97
	v_cvt_pk_bf16_f32 v176, v104, v105
	v_exp_f32_e32 v81, v81
	v_add_f32_e32 v96, v96, v97
	v_exp_f32_e32 v82, v82
	v_add_f32_e32 v104, v104, v105
	v_add_f32_e32 v96, v98, v96
	v_exp_f32_e32 v83, v83
	v_add_f32_e32 v104, v106, v104
	v_exp_f32_e32 v84, v84
	v_cvt_pk_bf16_f32 v181, v98, v99
	v_add_f32_e32 v96, v99, v96
	v_exp_f32_e32 v85, v85
	v_add_f32_e32 v104, v107, v104
	v_exp_f32_e32 v86, v86
	v_cvt_pk_bf16_f32 v177, v106, v107
	v_add_f32_e32 v96, v100, v96
	v_exp_f32_e32 v87, v87
	v_add_f32_e32 v104, v108, v104
	v_exp_f32_e32 v88, v88
	v_cvt_pk_bf16_f32 v182, v100, v101
	v_add_f32_e32 v96, v101, v96
	v_exp_f32_e32 v89, v89
	v_add_f32_e32 v104, v109, v104
	v_exp_f32_e32 v90, v90
	v_cvt_pk_bf16_f32 v178, v108, v109
	v_add_f32_e32 v96, v102, v96
	v_exp_f32_e32 v91, v91
	v_add_f32_e32 v104, v110, v104
	v_exp_f32_e32 v92, v92
	v_cvt_pk_bf16_f32 v183, v102, v103
	v_add_f32_e32 v96, v103, v96
	v_exp_f32_e32 v93, v93
	v_add_f32_e32 v104, v111, v104
	v_exp_f32_e32 v94, v94
	v_cvt_pk_bf16_f32 v179, v110, v111
	v_add_f32_e32 v96, v96, v104
	v_exp_f32_e32 v95, v95
	v_cvt_pk_bf16_f32 v172, v80, v81
	v_cvt_pk_bf16_f32 v168, v88, v89
	v_add_f32_e32 v80, v80, v81
	v_add_f32_e32 v88, v88, v89
	v_add_f32_e32 v80, v82, v80
	v_add_f32_e32 v88, v90, v88
	v_cvt_pk_bf16_f32 v173, v82, v83
	v_add_f32_e32 v80, v83, v80
	v_add_f32_e32 v88, v91, v88
	v_cvt_pk_bf16_f32 v169, v90, v91
	v_add_f32_e32 v80, v84, v80
	v_add_f32_e32 v88, v92, v88
	v_cvt_pk_bf16_f32 v174, v84, v85
	v_add_f32_e32 v80, v85, v80
	v_add_f32_e32 v88, v93, v88
	v_cvt_pk_bf16_f32 v170, v92, v93
	v_add_f32_e32 v80, v86, v80
	v_add_f32_e32 v88, v94, v88
	v_cvt_pk_bf16_f32 v175, v86, v87
	v_add_f32_e32 v80, v87, v80
	v_add_f32_e32 v88, v95, v88
	v_cvt_pk_bf16_f32 v171, v94, v95
	v_add_f32_e32 v80, v80, v88
	v_add_f32_e32 v185, v80, v96
	s_waitcnt vmcnt(3)
	s_cmpk_gt_u32 s64, 0x81
	s_cbranch_scc1 .LBB0_1195
	s_add_i32 s0, s51, 0x8000
	s_and_b32 s0, s0, 0x8000
	s_add_i32 s0, s0, 0
	v_add_u32_e32 v80, s0, v210
	s_waitcnt vmcnt(5)
	ds_write_b128 v80, v[132:135]
	v_add_u32_e32 v80, s0, v211
	s_add_i32 s0, s7, 0xffff
	s_mul_i32 s1, s0, 0xab
	s_bfe_u32 s1, s1, 0x70009
	s_mul_i32 s1, s1, 3
	s_sub_i32 s0, s0, s1
	s_and_b32 s0, s0, 0xff
	s_mulk_i32 s0, 0x2400
	s_waitcnt vmcnt(4)
	ds_write_b128 v80, v[128:131]
	v_add_u32_e32 v80, s0, v212
	s_waitcnt vmcnt(3)
	ds_write_b128 v80, v[136:139]

; #define SBAR() __builtin_amdgcn_sched_barrier(0)
; #define PK4(P, BASE, OUT) do { u32x4 w = {cvtpk_a(P[BASE + 0], P[BASE + 1]), cvtpk_a(P[BASE + 2], P[BASE + 3]), cvtpk_a(P[BASE + 4], P[BASE + 5]), cvtpk_a(P[BASE + 6], P[BASE + 7])}; \
;     OUT = *reinterpret_cast<bf16x8*>(&w); } while (0)
; #define SWAIT() asm volatile("s_waitcnt vmcnt(3)" ::: "memory")
; __device__ __forceinline__ float exp_pack(f32x16& p0, f32x16& p1, bf16x8& pa0, bf16x8& pa1, bf16x8& pa2, bf16x8& pa3) {
; #pragma unroll
;     for (int r = 0; r < 16; ++r) p0[r] = __builtin_amdgcn_exp2f(p0[r]);
; #pragma unroll
;     for (int r = 0; r < 16; ++r) p1[r] = __builtin_amdgcn_exp2f(p1[r]);
;     SBAR(); asm volatile("s_nop 1" ::: "memory"); SBAR();
;     ...
;     PK4(p0, 0, pa0); PK4(p0, 8, pa1); PK4(p1, 0, pa2); PK4(p1, 8, pa3);
;     ...
;     float ps0 = p0[0], ps1 = p1[0];
; #pragma unroll
;     for (int r = 1; r < 16; ++r) { ps0 += p0[r]; ps1 += p1[r]; }
;     float ps = ps0 + ps1;
;     { auto rr = __builtin_amdgcn_permlane32_swap(__float_as_uint(ps), __float_as_uint(ps), false, false);
;       ps = __uint_as_float(rr[0]) + __uint_as_float(rr[1]); }
;     return ps;
; template <bool MLA>
; __device__ __forceinline__ void attn_core(const bf16_t* __restrict__ Qb, const bf16_t* __restrict__ Kh, const bf16_t* __restrict__ Vh, int seq, char* lds,
;                                           f32x16 (&o)[Cfg<MLA>::NCB], const int wid  , const int g  ) {
;     ...
;         SWAIT(); if (j + 3 < NT) SWRITE(((j + 3) % 3) * SHM_K, ((j + 3) & 3) * SHM_V, SO);
.LBB0_1200:
	v_exp_f32_e32 v96, v96
	v_exp_f32_e32 v97, v97
	v_exp_f32_e32 v98, v98
	v_exp_f32_e32 v99, v99
	v_exp_f32_e32 v100, v100
	v_exp_f32_e32 v101, v101
	v_exp_f32_e32 v102, v102
	v_exp_f32_e32 v103, v103
	v_exp_f32_e32 v104, v104
	v_exp_f32_e32 v105, v105
	v_exp_f32_e32 v106, v106
	v_exp_f32_e32 v107, v107
	v_exp_f32_e32 v108, v108
	v_exp_f32_e32 v109, v109
	v_exp_f32_e32 v110, v110
	v_exp_f32_e32 v111, v111
	v_exp_f32_e32 v80, v80
	v_cvt_pk_bf16_f32 v180, v96, v97
	v_cvt_pk_bf16_f32 v176, v104, v105
	v_exp_f32_e32 v81, v81
	v_add_f32_e32 v96, v96, v97
	v_exp_f32_e32 v82, v82
	v_add_f32_e32 v104, v104, v105
	v_add_f32_e32 v96, v98, v96
	v_exp_f32_e32 v83, v83
	v_add_f32_e32 v104, v106, v104
	v_exp_f32_e32 v84, v84
	v_cvt_pk_bf16_f32 v181, v98, v99
	v_add_f32_e32 v96, v99, v96
	v_exp_f32_e32 v85, v85
	v_add_f32_e32 v104, v107, v104
	v_exp_f32_e32 v86, v86
	v_cvt_pk_bf16_f32 v177, v106, v107
	v_add_f32_e32 v96, v100, v96
	v_exp_f32_e32 v87, v87
	v_add_f32_e32 v104, v108, v104
	v_exp_f32_e32 v88, v88
	v_cvt_pk_bf16_f32 v182, v100, v101
	v_add_f32_e32 v96, v101, v96
	v_exp_f32_e32 v89, v89
	v_add_f32_e32 v104, v109, v104
	v_exp_f32_e32 v90, v90
	v_cvt_pk_bf16_f32 v178, v108, v109
	v_add_f32_e32 v96, v102, v96
	v_exp_f32_e32 v91, v91
	v_add_f32_e32 v104, v110, v104
	v_exp_f32_e32 v92, v92
	v_cvt_pk_bf16_f32 v183, v102, v103
	v_add_f32_e32 v96, v103, v96
	v_exp_f32_e32 v93, v93
	v_add_f32_e32 v104, v111, v104
	v_exp_f32_e32 v94, v94
	v_cvt_pk_bf16_f32 v179, v110, v111
	v_add_f32_e32 v96, v96, v104
	v_exp_f32_e32 v95, v95
	v_cvt_pk_bf16_f32 v172, v80, v81
	v_cvt_pk_bf16_f32 v168, v88, v89
	v_add_f32_e32 v80, v80, v81
	v_add_f32_e32 v88, v88, v89
	v_add_f32_e32 v80, v82, v80
	v_add_f32_e32 v88, v90, v88
	v_cvt_pk_bf16_f32 v173, v82, v83
	v_add_f32_e32 v80, v83, v80
	v_add_f32_e32 v88, v91, v88
	v_cvt_pk_bf16_f32 v169, v90, v91
	v_add_f32_e32 v80, v84, v80
	v_add_f32_e32 v88, v92, v88
	v_cvt_pk_bf16_f32 v174, v84, v85
	v_add_f32_e32 v80, v85, v80
	v_add_f32_e32 v88, v93, v88
	v_cvt_pk_bf16_f32 v170, v92, v93
	v_add_f32_e32 v80, v86, v80
	v_add_f32_e32 v88, v94, v88
	v_cvt_pk_bf16_f32 v175, v86, v87
	v_add_f32_e32 v80, v87, v80
	v_add_f32_e32 v88, v95, v88
	v_cvt_pk_bf16_f32 v171, v94, v95
	v_add_f32_e32 v80, v80, v88
	v_add_f32_e32 v80, v80, v96
	s_waitcnt vmcnt(3)
	s_cmpk_gt_u32 s64, 0x80
	s_cbranch_scc1 .LBB0_1180
	s_add_i32 s0, s65, 0
	v_add_u32_e32 v82, s0, v210
	s_waitcnt vmcnt(5)
	ds_write_b128 v82, v[140:143]
	v_add_u32_e32 v82, s0, v211
	s_mul_i32 s0, s7, 0xab
	s_bfe_u32 s0, s0, 0x70009
	s_mul_i32 s0, s0, 3
	s_sub_i32 s0, s7, s0
	s_and_b32 s0, s0, 0xff
	s_mulk_i32 s0, 0x2400
	s_waitcnt vmcnt(4)
	ds_write_b128 v82, v[144:147]
	v_add_u32_e32 v82, s0, v212
	s_waitcnt vmcnt(3)
	ds_write_b128 v82, v[148:151]
	s_branch .LBB0_1180

; #define SBAR() __builtin_amdgcn_sched_barrier(0)
; #define PK4(P, BASE, OUT) do { u32x4 w = {cvtpk_a(P[BASE + 0], P[BASE + 1]), cvtpk_a(P[BASE + 2], P[BASE + 3]), cvtpk_a(P[BASE + 4], P[BASE + 5]), cvtpk_a(P[BASE + 6], P[BASE + 7])}; \
;     OUT = *reinterpret_cast<bf16x8*>(&w); } while (0)
; #define SWAIT() asm volatile("s_waitcnt vmcnt(3)" ::: "memory")
; __device__ __forceinline__ float exp_pack(f32x16& p0, f32x16& p1, bf16x8& pa0, bf16x8& pa1, bf16x8& pa2, bf16x8& pa3) {
; #pragma unroll
;     for (int r = 0; r < 16; ++r) p0[r] = __builtin_amdgcn_exp2f(p0[r]);
; #pragma unroll
;     for (int r = 0; r < 16; ++r) p1[r] = __builtin_amdgcn_exp2f(p1[r]);
;     SBAR(); asm volatile("s_nop 1" ::: "memory"); SBAR();
;     ...
;     PK4(p0, 0, pa0); PK4(p0, 8, pa1); PK4(p1, 0, pa2); PK4(p1, 8, pa3);
;     ...
;     float ps0 = p0[0], ps1 = p1[0];
; #pragma unroll
;     for (int r = 1; r < 16; ++r) { ps0 += p0[r]; ps1 += p1[r]; }
;     float ps = ps0 + ps1;
;     { auto rr = __builtin_amdgcn_permlane32_swap(__float_as_uint(ps), __float_as_uint(ps), false, false);
;       ps = __uint_as_float(rr[0]) + __uint_as_float(rr[1]); }
;     return ps;
; template <bool MLA>
; __device__ __forceinline__ void attn_core(const bf16_t* __restrict__ Qb, const bf16_t* __restrict__ Kh, const bf16_t* __restrict__ Vh, int seq, char* lds,
;                                           f32x16 (&o)[Cfg<MLA>::NCB], const int wid  , const int g  ) {
;     ...
;         SWAIT(); if (j + 2 < NT) SWRITE(((j + 2) % 3) * SHM_K, ((j + 2) & 3) * SHM_V, SE);
.LBB0_1233:
	v_exp_f32_e32 v64, v64
	v_exp_f32_e32 v65, v65
	v_exp_f32_e32 v66, v66
	v_exp_f32_e32 v67, v67
	v_exp_f32_e32 v68, v68
	v_exp_f32_e32 v69, v69
	v_exp_f32_e32 v70, v70
	v_exp_f32_e32 v71, v71
	v_exp_f32_e32 v72, v72
	v_exp_f32_e32 v73, v73
	v_exp_f32_e32 v74, v74
	v_exp_f32_e32 v75, v75
	v_exp_f32_e32 v76, v76
	v_exp_f32_e32 v77, v77
	v_exp_f32_e32 v78, v78
	v_exp_f32_e32 v79, v79
	v_exp_f32_e32 v48, v48
	v_cvt_pk_bf16_f32 v140, v64, v65
	v_cvt_pk_bf16_f32 v136, v72, v73
	v_exp_f32_e32 v49, v49
	v_add_f32_e32 v64, v64, v65
	v_exp_f32_e32 v50, v50
	v_add_f32_e32 v72, v72, v73
	v_add_f32_e32 v64, v66, v64
	v_exp_f32_e32 v51, v51
	v_add_f32_e32 v72, v74, v72
	v_exp_f32_e32 v52, v52
	v_cvt_pk_bf16_f32 v141, v66, v67
	v_add_f32_e32 v64, v67, v64
	v_exp_f32_e32 v53, v53
	v_add_f32_e32 v72, v75, v72
	v_exp_f32_e32 v54, v54
	v_cvt_pk_bf16_f32 v137, v74, v75
	v_add_f32_e32 v64, v68, v64
	v_exp_f32_e32 v55, v55
	v_add_f32_e32 v72, v76, v72
	v_exp_f32_e32 v56, v56
	v_cvt_pk_bf16_f32 v142, v68, v69
	v_add_f32_e32 v64, v69, v64
	v_exp_f32_e32 v57, v57
	v_add_f32_e32 v72, v77, v72
	v_exp_f32_e32 v58, v58
	v_cvt_pk_bf16_f32 v138, v76, v77
	v_add_f32_e32 v64, v70, v64
	v_exp_f32_e32 v59, v59
	v_add_f32_e32 v72, v78, v72
	v_exp_f32_e32 v60, v60
	v_cvt_pk_bf16_f32 v143, v70, v71
	v_add_f32_e32 v64, v71, v64
	v_exp_f32_e32 v61, v61
	v_add_f32_e32 v72, v79, v72
	v_exp_f32_e32 v62, v62
	v_cvt_pk_bf16_f32 v139, v78, v79
	v_add_f32_e32 v64, v64, v72
	v_exp_f32_e32 v63, v63
	v_cvt_pk_bf16_f32 v132, v48, v49
	v_cvt_pk_bf16_f32 v128, v56, v57
	v_add_f32_e32 v48, v48, v49
	v_add_f32_e32 v56, v56, v57
	v_add_f32_e32 v48, v50, v48
	v_add_f32_e32 v56, v58, v56
	v_cvt_pk_bf16_f32 v133, v50, v51
	v_add_f32_e32 v48, v51, v48
	v_add_f32_e32 v56, v59, v56
	v_cvt_pk_bf16_f32 v129, v58, v59
	v_add_f32_e32 v48, v52, v48
	v_add_f32_e32 v56, v60, v56
	v_cvt_pk_bf16_f32 v134, v52, v53
	v_add_f32_e32 v48, v53, v48
	v_add_f32_e32 v56, v61, v56
	v_cvt_pk_bf16_f32 v130, v60, v61
	v_add_f32_e32 v48, v54, v48
	v_add_f32_e32 v56, v62, v56
	v_cvt_pk_bf16_f32 v135, v54, v55
	v_add_f32_e32 v48, v55, v48
	v_add_f32_e32 v56, v63, v56
	v_cvt_pk_bf16_f32 v131, v62, v63
	v_add_f32_e32 v48, v48, v56
	v_add_f32_e32 v159, v48, v64
	s_waitcnt vmcnt(3)
	s_cmpk_gt_u32 s61, 0x81
	s_cbranch_scc1 .LBB0_1236
	s_add_i32 s10, s60, 0xffffe000
	s_and_b32 s10, s10, 0x4000
	v_add_u32_e32 v48, s10, v145
	s_add_i32 s10, s51, 0xffff
	s_mul_i32 s11, s10, 0xab
	s_bfe_u32 s11, s11, 0x70009
	s_mul_i32 s11, s11, 3
	s_sub_i32 s10, s10, s11
	s_and_b32 s10, s10, 0xff
	s_mulk_i32 s10, 0x4400
	s_add_i32 s16, s10, 0
	s_waitcnt vmcnt(5)
	ds_write_b128 v48, v[112:115]
	v_add_u32_e32 v48, s16, v144
	s_and_b64 vcc, exec, s[4:5]
	s_waitcnt vmcnt(4)
	ds_write_b128 v48, v[108:111] offset:32768
	s_cbranch_vccnz .LBB0_1236
	v_add_u32_e32 v48, s16, v150
	s_waitcnt vmcnt(3)
	ds_write_b128 v48, v[104:107] offset:32768

; #define SBAR() __builtin_amdgcn_sched_barrier(0)
; #define PK4(P, BASE, OUT) do { u32x4 w = {cvtpk_a(P[BASE + 0], P[BASE + 1]), cvtpk_a(P[BASE + 2], P[BASE + 3]), cvtpk_a(P[BASE + 4], P[BASE + 5]), cvtpk_a(P[BASE + 6], P[BASE + 7])}; \
;     OUT = *reinterpret_cast<bf16x8*>(&w); } while (0)
; #define SWAIT() asm volatile("s_waitcnt vmcnt(3)" ::: "memory")
; __device__ __forceinline__ float exp_pack(f32x16& p0, f32x16& p1, bf16x8& pa0, bf16x8& pa1, bf16x8& pa2, bf16x8& pa3) {
; #pragma unroll
;     for (int r = 0; r < 16; ++r) p0[r] = __builtin_amdgcn_exp2f(p0[r]);
; #pragma unroll
;     for (int r = 0; r < 16; ++r) p1[r] = __builtin_amdgcn_exp2f(p1[r]);
;     SBAR(); asm volatile("s_nop 1" ::: "memory"); SBAR();
;     ...
;     PK4(p0, 0, pa0); PK4(p0, 8, pa1); PK4(p1, 0, pa2); PK4(p1, 8, pa3);
;     ...
;     float ps0 = p0[0], ps1 = p1[0];
; #pragma unroll
;     for (int r = 1; r < 16; ++r) { ps0 += p0[r]; ps1 += p1[r]; }
;     float ps = ps0 + ps1;
;     { auto rr = __builtin_amdgcn_permlane32_swap(__float_as_uint(ps), __float_as_uint(ps), false, false);
;       ps = __uint_as_float(rr[0]) + __uint_as_float(rr[1]); }
;     return ps;
; template <bool MLA>
; __device__ __forceinline__ void attn_core(const bf16_t* __restrict__ Qb, const bf16_t* __restrict__ Kh, const bf16_t* __restrict__ Vh, int seq, char* lds,
;                                           f32x16 (&o)[Cfg<MLA>::NCB], const int wid  , const int g  ) {
;     ...
;         SWAIT(); if (j + 3 < NT) SWRITE(((j + 3) % 3) * SHM_K, ((j + 3) & 3) * SHM_V, SO);
.LBB0_1241:
	v_exp_f32_e32 v64, v64
	v_exp_f32_e32 v65, v65
	v_exp_f32_e32 v66, v66
	v_exp_f32_e32 v67, v67
	v_exp_f32_e32 v68, v68
	v_exp_f32_e32 v69, v69
	v_exp_f32_e32 v70, v70
	v_exp_f32_e32 v71, v71
	v_exp_f32_e32 v72, v72
	v_exp_f32_e32 v73, v73
	v_exp_f32_e32 v74, v74
	v_exp_f32_e32 v75, v75
	v_exp_f32_e32 v76, v76
	v_exp_f32_e32 v77, v77
	v_exp_f32_e32 v78, v78
	v_exp_f32_e32 v79, v79
	v_exp_f32_e32 v48, v48
	v_cvt_pk_bf16_f32 v140, v64, v65
	v_cvt_pk_bf16_f32 v136, v72, v73
	v_exp_f32_e32 v49, v49
	v_add_f32_e32 v64, v64, v65
	v_exp_f32_e32 v50, v50
	v_add_f32_e32 v72, v72, v73
	v_add_f32_e32 v64, v66, v64
	v_exp_f32_e32 v51, v51
	v_add_f32_e32 v72, v74, v72
	v_exp_f32_e32 v52, v52
	v_cvt_pk_bf16_f32 v141, v66, v67
	v_add_f32_e32 v64, v67, v64
	v_exp_f32_e32 v53, v53
	v_add_f32_e32 v72, v75, v72
	v_exp_f32_e32 v54, v54
	v_cvt_pk_bf16_f32 v137, v74, v75
	v_add_f32_e32 v64, v68, v64
	v_exp_f32_e32 v55, v55
	v_add_f32_e32 v72, v76, v72
	v_exp_f32_e32 v56, v56
	v_cvt_pk_bf16_f32 v142, v68, v69
	v_add_f32_e32 v64, v69, v64
	v_exp_f32_e32 v57, v57
	v_add_f32_e32 v72, v77, v72
	v_exp_f32_e32 v58, v58
	v_cvt_pk_bf16_f32 v138, v76, v77
	v_add_f32_e32 v64, v70, v64
	v_exp_f32_e32 v59, v59
	v_add_f32_e32 v72, v78, v72
	v_exp_f32_e32 v60, v60
	v_cvt_pk_bf16_f32 v143, v70, v71
	v_add_f32_e32 v64, v71, v64
	v_exp_f32_e32 v61, v61
	v_add_f32_e32 v72, v79, v72
	v_exp_f32_e32 v62, v62
	v_cvt_pk_bf16_f32 v139, v78, v79
	v_add_f32_e32 v64, v64, v72
	v_exp_f32_e32 v63, v63
	v_cvt_pk_bf16_f32 v132, v48, v49
	v_cvt_pk_bf16_f32 v128, v56, v57
	v_add_f32_e32 v48, v48, v49
	v_add_f32_e32 v56, v56, v57
	v_add_f32_e32 v48, v50, v48
	v_add_f32_e32 v56, v58, v56
	v_cvt_pk_bf16_f32 v133, v50, v51
	v_add_f32_e32 v48, v51, v48
	v_add_f32_e32 v56, v59, v56
	v_cvt_pk_bf16_f32 v129, v58, v59
	v_add_f32_e32 v48, v52, v48
	v_add_f32_e32 v56, v60, v56
	v_cvt_pk_bf16_f32 v134, v52, v53
	v_add_f32_e32 v48, v53, v48
	v_add_f32_e32 v56, v61, v56
	v_cvt_pk_bf16_f32 v130, v60, v61
	v_add_f32_e32 v48, v54, v48
	v_add_f32_e32 v56, v62, v56
	v_cvt_pk_bf16_f32 v135, v54, v55
	v_add_f32_e32 v48, v55, v48
	v_add_f32_e32 v56, v63, v56
	v_cvt_pk_bf16_f32 v131, v62, v63
	v_add_f32_e32 v48, v48, v56
	v_add_f32_e32 v48, v48, v64
	s_waitcnt vmcnt(3)
	s_cmpk_gt_u32 s61, 0x80
	s_cbranch_scc1 .LBB0_1227
	s_mul_i32 s10, s51, 0xab
	s_bfe_u32 s10, s10, 0x70009
	s_mul_i32 s10, s10, 3
	s_sub_i32 s10, s51, s10
	s_and_b32 s10, s10, 0xff
	s_mulk_i32 s10, 0x4400
	v_add_u32_e32 v50, s62, v145
	s_add_i32 s16, s10, 0
	s_waitcnt vmcnt(5)
	ds_write_b128 v50, v[116:119]
	v_add_u32_e32 v50, s16, v144
	s_and_b64 vcc, exec, s[4:5]
	s_waitcnt vmcnt(4)
	ds_write_b128 v50, v[124:127] offset:32768
	s_cbranch_vccnz .LBB0_1227
	v_add_u32_e32 v50, s16, v150
	s_waitcnt vmcnt(3)
	ds_write_b128 v50, v[120:123] offset:32768
	s_branch .LBB0_1227
